# FoX tile loop: K-fragment LDS reads and the cumsum tail read issued at the loop top, before the next-tile DMA issue block (overlap LDS latency with DMA issue)
# baseline (speedup 1.0000x reference)
; template <bool SBK>
; __device__ __forceinline__ void attn_unit(const Args& a, int l, LAS char* lds, int b, int h8, int P0, int orow0, int nvalid) {
;     ...
;     for (;;) {
;         const int kb = (jmax - t) * 64; const bool more = (t + 1 < NT);
;         const int vn = vb == 2 ? 0 : vb + 1, vnn = vn == 2 ? 0 : vn + 1;
;         if (t + 2 < NT) GISSUE(vnn);
;         const bool act = SBK ? (kb < qlo + 31) : (kb <= qlo + 31);
;         if (act) {
;             qkt(p0, p1, K_lds + vb * SHM_K, r32, hi, qr);
;     ...
;         else { const float cl_ = more ? cm_l[kb - 1] : 0.f;
.LBB0_567:
	s_sub_i32 s5, s7, s23
	s_lshl_b32 s27, s5, 6
	s_lshl_b32 s5, s27, 2
	s_add_i32 s5, s5, 0x1887c
	v_mov_b32_e32 v220, s5
	ds_read_b32 v220, v220
	s_cmp_gt_i32 s27, s8
	s_cbranch_scc1 .Lfx_top_noact
	s_lshl_b32 s35, s4, 14
	v_add_u32_e32 v0, s35, v174
	v_add_u32_e32 v14, v0, v176
	v_add_u32_e32 v15, v0, v177
	v_add_u32_e32 v88, v0, v178
	v_add_u32_e32 v0, v0, v179
	ds_read_b128 v[2:5], v14 offset:49152
	ds_read_b128 v[208:211], v15 offset:49152
	ds_read_b128 v[212:215], v88 offset:49152
	ds_read_b128 v[216:219], v0 offset:49152
	ds_read_b128 v[6:9], v14 offset:49280
	ds_read_b128 v[10:13], v15 offset:49280
	ds_read_b128 v[80:83], v88 offset:49280
	ds_read_b128 v[84:87], v0 offset:49280
	ds_read_b128 v[188:191], v88 offset:57344
	ds_read_b128 v[196:199], v0 offset:57344
	ds_read_b128 v[184:187], v15 offset:57472
	ds_read_b128 v[192:195], v88 offset:57472
	ds_read_b128 v[200:203], v0 offset:57472

; template <bool SBK>
; __device__ __forceinline__ void attn_unit(const Args& a, int l, LAS char* lds, int b, int h8, int P0, int orow0, int nvalid) {
;     ...
;             qkt(p0, p1, K_lds + vb * SHM_K, r32, hi, qr);
;             const int dq = qpos - kb - 4 * hi;
;             if constexpr (SBK) {
;                 const bool needmask = (kb + 63 >= qlo);
;                 f32x16 l0, l1;
; #pragma unroll
;  for (int r = 0; r < 16; ++r) { const int c = (r & 3) + 8 * (r >> 2);
;                     float z = p0[r]; float lv = -(fmaxf(z, 0.f) + __builtin_amdgcn_logf(1.0f + __builtin_amdgcn_exp2f(-fabsf(z)))); if (needmask && (dq - c < 1)) lv = 0.f; l0[r] = lv;
;                     z = p1[r]; lv = -(fmaxf(z, 0.f) + __builtin_amdgcn_logf(1.0f + __builtin_amdgcn_exp2f(-fabsf(z)))); if (needmask && (dq - c - 32 < 1)) lv = 0.f; l1[r] = lv; }
;                 float gs[8], pg[8], aft[8];
; #pragma unroll
;  for (int i = 0; i < 4; ++i) { gs[i] = (l0[4 * i] + l0[4 * i + 1]) + (l0[4 * i + 2] + l0[4 * i + 3]); gs[4 + i] = (l1[4 * i] + l1[4 * i + 1]) + (l1[4 * i + 2] + l1[4 * i + 3]); }
; #pragma unroll
;  for (int i = 0; i < 8; ++i) pg[i] = pair_other(gs[i], hi);
;                 float run = R;
; #pragma unroll
;  for (int i = 7; i >= 0; --i) { aft[i] = run + (hi ? 0.f : pg[i]); run += gs[i] + pg[i]; }
;                 R = run;
; #pragma unroll
;  for (int i = 0; i < 4; ++i) { float c0 = aft[i], c1 = aft[4 + i];
; #pragma unroll
;  for (int e = 3; e >= 0; --e) { const int r = 4 * i + e; const int c = (r & 3) + 8 * (r >> 2);
;                         c0 += l0[r]; float av = __builtin_amdgcn_exp2f(p0[r] + c0); if (needmask && (dq - c < 1)) av = 0.f; p0[r] = av;
;                         c1 += l1[r]; av = __builtin_amdgcn_exp2f(p1[r] + c1); if (needmask && (dq - c - 32 < 1)) av = 0.f; p1[r] = av; } }
;             } else {
;                 const bool needmask = (kb + 63 > qlo); const float NEG = -__builtin_inff();
;                 __builtin_amdgcn_sched_barrier(0);
;                 { const LAS float* cb_ = cm_l + kb + 4 * hi;
; #pragma unroll
;  for (int g = 0; g < 4; ++g) { const f32x4 c0 = *(const LAS f32x4*)(cb_ + 8 * g);
; #pragma unroll
;  for (int e = 0; e < 4; ++e) p0[4 * g + e] -= c0[e]; }
;                   __builtin_amdgcn_sched_barrier(0);
; #pragma unroll
;  for (int g = 0; g < 4; ++g) { const f32x4 c1 = *(const LAS f32x4*)(cb_ + 32 + 8 * g);
; #pragma unroll
.LBB0_569:
	s_sub_i32 s5, s7, s23
	s_lshl_b32 s27, s5, 6
	s_cmp_gt_i32 s27, s8
	s_cbranch_scc1 .LBB0_577
	s_or_b32 s4, s27, 63
	s_waitcnt lgkmcnt(12)
	v_mfma_f32_32x32x16_bf16 v[96:111], v[2:5], v[112:115], 0
	s_waitcnt lgkmcnt(11)
	v_mfma_f32_32x32x16_bf16 v[96:111], v[208:211], v[116:119], v[96:111]
	s_waitcnt lgkmcnt(10)
	v_mfma_f32_32x32x16_bf16 v[96:111], v[212:215], v[120:123], v[96:111]
	s_waitcnt lgkmcnt(9)
	v_mfma_f32_32x32x16_bf16 v[96:111], v[216:219], v[124:127], v[96:111]
	s_waitcnt lgkmcnt(8)
	v_mfma_f32_32x32x16_bf16 v[96:111], v[6:9], v[128:131], v[96:111]
	s_waitcnt lgkmcnt(7)
	v_mfma_f32_32x32x16_bf16 v[96:111], v[10:13], v[132:135], v[96:111]
	ds_read_b128 v[2:5], v14 offset:57344
	ds_read_b128 v[10:13], v15 offset:57344
	ds_read_b128 v[6:9], v14 offset:57472
	s_waitcnt lgkmcnt(9)
	v_mfma_f32_32x32x16_bf16 v[96:111], v[80:83], v[136:139], v[96:111]
	s_waitcnt lgkmcnt(8)
	v_mfma_f32_32x32x16_bf16 v[96:111], v[84:87], v[140:143], v[96:111]
	s_waitcnt lgkmcnt(2)
	v_mfma_f32_32x32x16_bf16 v[80:95], v[2:5], v[112:115], 0
	v_lshl_add_u32 v0, s27, 2, v180
	s_waitcnt lgkmcnt(1)
	v_mfma_f32_32x32x16_bf16 v[80:95], v[10:13], v[116:119], v[80:95]
	v_mfma_f32_32x32x16_bf16 v[80:95], v[188:191], v[120:123], v[80:95]
	v_mfma_f32_32x32x16_bf16 v[80:95], v[196:199], v[124:127], v[80:95]
	s_waitcnt lgkmcnt(0)
	v_mfma_f32_32x32x16_bf16 v[80:95], v[6:9], v[128:131], v[80:95]
	v_mfma_f32_32x32x16_bf16 v[80:95], v[184:187], v[132:135], v[80:95]
	v_mfma_f32_32x32x16_bf16 v[80:95], v[192:195], v[136:139], v[80:95]
	ds_read_b128 v[184:187], v0
	ds_read_b128 v[188:191], v0 offset:32
	ds_read_b128 v[192:195], v0 offset:64
	ds_read_b128 v[196:199], v0 offset:96
	v_mfma_f32_32x32x16_bf16 v[80:95], v[200:203], v[140:143], v[80:95]
	ds_read_b128 v[2:5], v0 offset:224
	ds_read_b128 v[6:9], v0 offset:192
	ds_read_b128 v[200:203], v0 offset:128
	ds_read_b128 v[204:207], v0 offset:160
	s_waitcnt lgkmcnt(0)
	v_sub_f32_e32 v97, v97, v185
	s_nop 5
	v_sub_f32_e32 v15, v95, v5
	v_sub_f32_e32 v14, v94, v4
	v_sub_f32_e32 v13, v93, v3
	v_sub_f32_e32 v12, v92, v2
	v_sub_f32_e32 v11, v91, v9
	v_sub_f32_e32 v10, v90, v8
	v_sub_f32_e32 v9, v89, v7
	v_sub_f32_e32 v8, v88, v6
	v_sub_f32_e32 v7, v87, v207
	v_sub_f32_e32 v6, v86, v206
	v_sub_f32_e32 v5, v85, v205
	v_sub_f32_e32 v4, v84, v204
	v_sub_f32_e32 v3, v83, v203
	v_sub_f32_e32 v2, v82, v202
	v_sub_f32_e32 v91, v81, v201
	v_sub_f32_e32 v0, v80, v200
	v_sub_f32_e32 v81, v111, v199
	v_sub_f32_e32 v80, v110, v198
	v_sub_f32_e32 v83, v109, v197
	v_sub_f32_e32 v82, v108, v196
	v_sub_f32_e32 v85, v107, v195
	v_sub_f32_e32 v84, v106, v194
	v_sub_f32_e32 v87, v105, v193
	v_sub_f32_e32 v86, v104, v192
	v_sub_f32_e32 v89, v103, v191
	v_sub_f32_e32 v88, v102, v190
	v_sub_f32_e32 v93, v101, v189
	v_sub_f32_e32 v90, v100, v188
	v_sub_f32_e32 v95, v99, v187
	v_sub_f32_e32 v92, v98, v186
	v_sub_f32_e32 v94, v96, v184
	s_cmp_le_i32 s4, s31
	s_cbranch_scc1 .LBB0_572
	v_or_b32_e32 v96, s27, v172
	v_sub_u32_e32 v98, v155, v96
	v_cmp_lt_i32_e32 vcc, -1, v98
	v_xad_u32 v96, v96, -1, v155
	s_nop 0
	v_cndmask_b32_e32 v94, v245, v94, vcc
	v_cmp_lt_i32_e32 vcc, 31, v98
	s_nop 1
	v_cndmask_b32_e32 v0, v245, v0, vcc
	v_cmp_lt_i32_e32 vcc, -1, v96
	s_nop 1
	v_cndmask_b32_e32 v97, v245, v97, vcc
	v_cmp_lt_i32_e32 vcc, 31, v96
	v_or_b32_e32 v96, s27, v170
	v_sub_u32_e32 v96, v155, v96
	v_cndmask_b32_e32 v91, v245, v91, vcc
	v_cmp_lt_i32_e32 vcc, -1, v96
	s_nop 1
	v_cndmask_b32_e32 v92, v245, v92, vcc
	v_cmp_lt_i32_e32 vcc, 31, v96
	v_or_b32_e32 v96, s27, v169
	v_sub_u32_e32 v96, v155, v96
	v_cndmask_b32_e32 v2, v245, v2, vcc
	v_cmp_lt_i32_e32 vcc, -1, v96
	s_nop 1
	v_cndmask_b32_e32 v95, v245, v95, vcc
	v_cmp_lt_i32_e32 vcc, 31, v96
	v_or_b32_e32 v96, s27, v168
	v_sub_u32_e32 v96, v155, v96
	v_cndmask_b32_e32 v3, v245, v3, vcc
	v_cmp_lt_i32_e32 vcc, -1, v96
	s_nop 1
	v_cndmask_b32_e32 v90, v245, v90, vcc
	v_cmp_lt_i32_e32 vcc, 31, v96
	v_or_b32_e32 v96, s27, v167
	v_sub_u32_e32 v96, v155, v96
	v_cndmask_b32_e32 v4, v245, v4, vcc
	v_cmp_lt_i32_e32 vcc, -1, v96
	s_nop 1
	v_cndmask_b32_e32 v93, v245, v93, vcc
	v_cmp_lt_i32_e32 vcc, 31, v96
	v_or_b32_e32 v96, s27, v165
	v_sub_u32_e32 v96, v155, v96
	v_cndmask_b32_e32 v5, v245, v5, vcc
	v_cmp_lt_i32_e32 vcc, -1, v96
	s_nop 1
	v_cndmask_b32_e32 v88, v245, v88, vcc
	v_cmp_lt_i32_e32 vcc, 31, v96
	v_or_b32_e32 v96, s27, v164
	v_sub_u32_e32 v96, v155, v96
	v_cndmask_b32_e32 v6, v245, v6, vcc
	v_cmp_lt_i32_e32 vcc, -1, v96
	s_nop 1
	v_cndmask_b32_e32 v89, v245, v89, vcc
	v_cmp_lt_i32_e32 vcc, 31, v96
	v_or_b32_e32 v96, s27, v163
	v_sub_u32_e32 v96, v155, v96
	v_cndmask_b32_e32 v7, v245, v7, vcc
	v_cmp_lt_i32_e32 vcc, -1, v96
	s_nop 1
	v_cndmask_b32_e32 v86, v245, v86, vcc
	v_cmp_lt_i32_e32 vcc, 31, v96
	v_or_b32_e32 v96, s27, v162
	v_sub_u32_e32 v96, v155, v96
	v_cndmask_b32_e32 v8, v245, v8, vcc
	v_cmp_lt_i32_e32 vcc, -1, v96
	s_nop 1
	v_cndmask_b32_e32 v87, v245, v87, vcc
	v_cmp_lt_i32_e32 vcc, 31, v96
	v_or_b32_e32 v96, s27, v161
	v_sub_u32_e32 v96, v155, v96
	v_cndmask_b32_e32 v9, v245, v9, vcc
	v_cmp_lt_i32_e32 vcc, -1, v96
	s_nop 1
	v_cndmask_b32_e32 v84, v245, v84, vcc
	v_cmp_lt_i32_e32 vcc, 31, v96
	v_or_b32_e32 v96, s27, v160
	v_sub_u32_e32 v96, v155, v96
	v_cndmask_b32_e32 v10, v245, v10, vcc
	v_cmp_lt_i32_e32 vcc, -1, v96
	s_nop 1
	v_cndmask_b32_e32 v85, v245, v85, vcc
	v_cmp_lt_i32_e32 vcc, 31, v96
	v_or_b32_e32 v96, s27, v159
	v_sub_u32_e32 v96, v155, v96
	v_cndmask_b32_e32 v11, v245, v11, vcc
	v_cmp_lt_i32_e32 vcc, -1, v96
	s_nop 1
	v_cndmask_b32_e32 v82, v245, v82, vcc
	v_cmp_lt_i32_e32 vcc, 31, v96
	v_or_b32_e32 v96, s27, v158
	v_sub_u32_e32 v96, v155, v96
	v_cndmask_b32_e32 v12, v245, v12, vcc
	v_cmp_lt_i32_e32 vcc, -1, v96
	s_nop 1
	v_cndmask_b32_e32 v83, v245, v83, vcc
	v_cmp_lt_i32_e32 vcc, 31, v96
	v_or_b32_e32 v96, s27, v157
	v_sub_u32_e32 v96, v155, v96
	v_cndmask_b32_e32 v13, v245, v13, vcc
	v_cmp_lt_i32_e32 vcc, -1, v96
	s_nop 1
	v_cndmask_b32_e32 v80, v245, v80, vcc
	v_cmp_lt_i32_e32 vcc, 31, v96
	v_or_b32_e32 v96, s27, v156
	v_sub_u32_e32 v96, v155, v96
	v_cndmask_b32_e32 v14, v245, v14, vcc
	v_cmp_lt_i32_e32 vcc, -1, v96
	s_nop 1
	v_cndmask_b32_e32 v81, v245, v81, vcc
	v_cmp_lt_i32_e32 vcc, 31, v96
	s_nop 1
	v_cndmask_b32_e32 v15, v245, v15, vcc

; template <bool SBK>
; __device__ __forceinline__ void attn_unit(const Args& a, int l, LAS char* lds, int b, int h8, int P0, int orow0, int nvalid) {
;     ...
;         else { const float cl_ = more ? cm_l[kb - 1] : 0.f;
;                const bool alive = __any(qbound - cl_ - m_reg > FOX_EXIT); if (lane == 0) flag[(t & 1) * 8 + wid] = alive ? 1u : 0u; }
.LBB0_578:
	v_mov_b32_e32 v0, v220
